# up GEMM: first two K-loop waits after an epilogue relaxed to vmcnt(24) (the 16 epilogue stores no longer gate the first two MFMA phases of the next tile); no merge stagger
# speedup vs baseline: 1.0068x; 1.0068x over previous
.LBB0_865:
	s_cmp_lt_i32 s76, 11
	s_cselect_b64 s[8:9], -1, 0
	s_and_b64 s[4:5], s[8:9], s[46:47]
	s_andn2_b64 vcc, exec, s[4:5]
	s_cbranch_vccnz .LBB0_882
	s_mov_b32 s99, 0
	s_cmpk_gt_i32 s2, 0x15ff
	s_mov_b64 s[6:7], s[0:1]
	v_readfirstlane_b32 s16, v196
	s_waitcnt vmcnt(0) lgkmcnt(0)
	s_barrier
	s_cbranch_scc1 .LBB0_882
	v_lshrrev_b32_e32 v2, 1, v196
	v_lshrrev_b32_e32 v3, 5, v196
	v_and_b32_e32 v2, 24, v2
	v_and_b32_e32 v3, 4, v3
	s_load_dwordx2 s[10:11], s[6:7], 0xe0
	v_lshlrev_b32_e32 v0, 4, v196
	v_and_b32_e32 v1, 32, v196
	v_or3_b32 v2, v3, v223, v2
	v_lshrrev_b32_e32 v3, 3, v196
	s_movk_i32 s3, 0x70
	v_bitop3_b32 v8, v0, v1, 48 bitop3:0x6c
	v_and_b32_e32 v9, 64, v196
	v_and_or_b32 v4, v3, s3, v222
	s_movk_i32 s3, 0x60
	v_add_u32_e32 v10, 0x2000, v0
	v_or_b32_e32 v1, v8, v9
	v_and_or_b32 v3, v3, s3, v2
	v_lshrrev_b32_e32 v0, 7, v10
	s_movk_i32 s3, 0xf0
	v_lshl_or_b32 v130, v3, 11, v1
	v_and_or_b32 v3, v0, s3, v222
	s_movk_i32 s3, 0xe0
	v_and_or_b32 v0, v0, s3, v2
	s_waitcnt lgkmcnt(0)
	s_add_u32 s3, s10, 0x5200e00
	s_addc_u32 s36, s11, 0
	s_add_u32 s37, s10, 0x1600000
	s_addc_u32 s39, s11, 0
	s_ashr_i32 s47, s2, 31
	s_lshr_b32 s6, s47, 29
	s_add_i32 s6, s2, s6
	s_lshr_b32 s4, s16, 6
	s_ashr_i32 s7, s6, 3
	s_and_b32 s6, s6, -8
	s_lshr_b32 s5, s16, 8
	s_lshl_b32 s46, s4, 10
	s_sub_i32 s6, s2, s6
	s_cmp_lt_i32 s6, 0
	s_movk_i32 s48, 0x2c1
	s_cselect_b32 s12, s48, 0x2c0
	s_mul_i32 s6, s6, s12
	s_add_i32 s6, s6, s7
	s_mul_hi_i32 s7, s6, 0x2e8ba2e9
	s_lshr_b32 s12, s7, 31
	s_ashr_i32 s7, s7, 5
	s_add_i32 s7, s7, s12
	s_lshl_b32 s12, s7, 3
	s_mulk_i32 s7, 0xb0
	s_sub_i32 s7, s6, s7
	s_sext_i32_i16 s6, s7
	s_bfe_u32 s6, s6, 0x3001c
	s_add_i32 s13, s7, s6
	s_sext_i32_i16 s6, s13
	s_and_b32 s13, s13, 0xfff8
	s_sub_i32 s7, s7, s13
	s_sext_i32_i16 s7, s7
	s_lshr_b32 s6, s6, 3
	s_add_i32 s26, s12, s7
	s_ashr_i32 s27, s26, 31
	s_bfe_i64 s[14:15], s[6:7], 0x100000
	s_lshl_b64 s[12:13], s[26:27], 19
	s_lshl_b64 s[14:15], s[14:15], 19
	s_add_u32 s28, s37, s14
	s_addc_u32 s29, s39, s15
	s_add_i32 s27, s46, 0
	s_add_i32 m0, s27, 0x10000
	v_lshl_or_b32 v134, v0, 11, v1
	global_load_lds_dwordx4 v130, s[28:29]
	s_add_i32 m0, s27, 0x12000
	s_add_u32 s14, s28, 0x40000
	global_load_lds_dwordx4 v134, s[28:29]
	s_addc_u32 s15, s29, 0
	s_add_i32 m0, s27, 0x14000
	v_lshl_or_b32 v128, v4, 11, v1
	global_load_lds_dwordx4 v130, s[14:15]
	s_add_i32 m0, s27, 0x16000
	s_add_u32 s30, s3, s12
	s_addc_u32 s31, s36, s13
	s_add_i32 s49, s27, 0x2000
	global_load_lds_dwordx4 v134, s[14:15]
	s_mov_b32 m0, s27
	s_add_u32 s12, s30, 0x40000
	v_lshl_or_b32 v132, v3, 11, v1
	global_load_lds_dwordx4 v128, s[30:31]
	s_mov_b32 m0, s49
	s_addc_u32 s13, s31, 0
	s_add_i32 s50, s27, 0x4000
	global_load_lds_dwordx4 v132, s[30:31]
	s_mov_b32 m0, s50
	s_add_i32 s51, s27, 0x6000
	global_load_lds_dwordx4 v128, s[12:13]
	s_mov_b32 m0, s51
	v_mov_b32_e32 v131, 0
	global_load_lds_dwordx4 v132, s[12:13]
	v_mov_b32_e32 v135, v131
	v_mov_b32_e32 v129, v131
	v_mov_b32_e32 v133, v131
	s_cmp_eq_u32 s5, 1
	s_mov_b32 s52, 0
	v_lshl_add_u64 v[6:7], s[28:29], 0, v[130:131]
	v_lshl_add_u64 v[4:5], s[28:29], 0, v[134:135]
	v_lshl_add_u64 v[0:1], s[30:31], 0, v[128:129]
	s_cselect_b64 s[12:13], -1, 0
	s_cmp_lg_u32 s5, 1
	v_lshl_add_u64 v[2:3], s[30:31], 0, v[132:133]
	s_cbranch_scc1 .LBB0_869
	s_barrier

.LBB0_875:
	ds_read_b128 v[152:155], v149
	ds_read_b128 v[156:159], v149 offset:1024
	ds_read_b128 v[160:163], v149 offset:2048
	ds_read_b128 v[164:167], v149 offset:3072
	ds_read_b128 v[168:171], v150
	ds_read_b128 v[172:175], v150 offset:1024
	ds_read_b128 v[176:179], v150 offset:2048
	ds_read_b128 v[180:183], v150 offset:3072
	s_add_u32 s4, s28, 0xfffc0080
	s_addc_u32 s5, s29, -1
	s_cmp_eq_u32 s67, 12
	s_cselect_b32 s35, s21, s5
	s_cselect_b32 s34, s63, s4
	s_cselect_b32 s31, s19, s66
	s_cselect_b32 s30, s64, s65
	v_lshl_add_u64 v[144:145], s[28:29], 0, v[138:139]
	s_add_i32 m0, s27, 0xc000
	ds_read_b128 v[184:187], v151
	ds_read_b128 v[188:191], v151 offset:1024
	ds_read_b128 v[192:195], v151 offset:2048
	ds_read_b128 v[198:201], v151 offset:3072
	ds_read_b128 v[202:205], v151 offset:4096
	ds_read_b128 v[206:209], v151 offset:5120
	ds_read_b128 v[210:213], v151 offset:6144
	ds_read_b128 v[214:217], v151 offset:7168
	global_load_lds_dwordx4 v[144:145], off
	v_lshl_add_u64 v[144:145], s[28:29], 0, v[136:137]
	s_add_i32 m0, s27, 0xe000
	s_nop 0
	global_load_lds_dwordx4 v[144:145], off
	s_cmp_eq_u32 s99, 0
	s_cbranch_scc1 .Lw10_0n
	s_waitcnt vmcnt(24)
	s_branch .Lw10_0d
.Lw10_0n:
	s_waitcnt vmcnt(8)
.Lw10_0d:
	s_waitcnt lgkmcnt(0)
	s_barrier
	s_setprio 1
	s_waitcnt lgkmcnt(0)
	v_mfma_f32_16x16x32_bf16 v[124:127], v[152:155], v[184:187], v[124:127]
	v_mfma_f32_16x16x32_bf16 v[120:123], v[160:163], v[184:187], v[120:123]
	v_mfma_f32_16x16x32_bf16 v[116:119], v[152:155], v[192:195], v[116:119]
	v_mfma_f32_16x16x32_bf16 v[108:111], v[160:163], v[192:195], v[108:111]
	v_mfma_f32_16x16x32_bf16 v[100:103], v[152:155], v[202:205], v[100:103]
	v_mfma_f32_16x16x32_bf16 v[92:95], v[160:163], v[202:205], v[92:95]
	v_mfma_f32_16x16x32_bf16 v[84:87], v[152:155], v[210:213], v[84:87]
	v_mfma_f32_16x16x32_bf16 v[76:79], v[160:163], v[210:213], v[76:79]
	v_mfma_f32_16x16x32_bf16 v[124:127], v[156:159], v[188:191], v[124:127]
	v_mfma_f32_16x16x32_bf16 v[120:123], v[164:167], v[188:191], v[120:123]
	v_mfma_f32_16x16x32_bf16 v[116:119], v[156:159], v[198:201], v[116:119]
	v_mfma_f32_16x16x32_bf16 v[108:111], v[164:167], v[198:201], v[108:111]
	v_mfma_f32_16x16x32_bf16 v[100:103], v[156:159], v[206:209], v[100:103]
	v_mfma_f32_16x16x32_bf16 v[92:95], v[164:167], v[206:209], v[92:95]
	v_mfma_f32_16x16x32_bf16 v[84:87], v[156:159], v[214:217], v[84:87]
	v_mfma_f32_16x16x32_bf16 v[76:79], v[164:167], v[214:217], v[76:79]
	s_setprio 0
	s_setprio 1
	v_mfma_f32_16x16x32_bf16 v[112:115], v[168:171], v[184:187], v[112:115]
	v_mfma_f32_16x16x32_bf16 v[104:107], v[176:179], v[184:187], v[104:107]
	v_mfma_f32_16x16x32_bf16 v[96:99], v[168:171], v[192:195], v[96:99]
	v_mfma_f32_16x16x32_bf16 v[88:91], v[176:179], v[192:195], v[88:91]
	v_mfma_f32_16x16x32_bf16 v[80:83], v[168:171], v[202:205], v[80:83]
	v_mfma_f32_16x16x32_bf16 v[72:75], v[176:179], v[202:205], v[72:75]
	v_mfma_f32_16x16x32_bf16 v[68:71], v[168:171], v[210:213], v[68:71]
	v_mfma_f32_16x16x32_bf16 v[64:67], v[176:179], v[210:213], v[64:67]
	v_mfma_f32_16x16x32_bf16 v[112:115], v[172:175], v[188:191], v[112:115]
	v_mfma_f32_16x16x32_bf16 v[104:107], v[180:183], v[188:191], v[104:107]
	v_mfma_f32_16x16x32_bf16 v[96:99], v[172:175], v[198:201], v[96:99]
	v_mfma_f32_16x16x32_bf16 v[88:91], v[180:183], v[198:201], v[88:91]
	v_mfma_f32_16x16x32_bf16 v[80:83], v[172:175], v[206:209], v[80:83]
	v_mfma_f32_16x16x32_bf16 v[72:75], v[180:183], v[206:209], v[72:75]
	v_mfma_f32_16x16x32_bf16 v[68:71], v[172:175], v[214:217], v[68:71]
	v_mfma_f32_16x16x32_bf16 v[64:67], v[180:183], v[214:217], v[64:67]
	s_setprio 0
	s_barrier
	s_add_i32 s4, s58, s46
	v_lshl_add_u64 v[144:145], s[30:31], 0, v[130:131]
	s_mov_b32 m0, s4
	ds_read_b128 v[184:187], v151 offset:16384
	ds_read_b128 v[188:191], v151 offset:17408
	ds_read_b128 v[192:195], v151 offset:18432
	ds_read_b128 v[198:201], v151 offset:19456
	ds_read_b128 v[202:205], v151 offset:20480
	ds_read_b128 v[206:209], v151 offset:21504
	ds_read_b128 v[210:213], v151 offset:22528
	ds_read_b128 v[214:217], v151 offset:23552
	global_load_lds_dwordx4 v[144:145], off
	s_add_i32 m0, s4, 0x2000
	s_add_u32 s4, s30, 0x40000
	v_lshl_add_u64 v[218:219], s[30:31], 0, v[134:135]
	s_addc_u32 s5, s31, 0
	s_add_i32 s33, s59, s46
	global_load_lds_dwordx4 v[218:219], off
	v_lshl_add_u64 v[220:221], s[4:5], 0, v[130:131]
	s_mov_b32 m0, s33
	v_lshl_add_u64 v[224:225], s[34:35], 0, v[132:133]
	global_load_lds_dwordx4 v[220:221], off
	v_lshl_add_u64 v[220:221], s[4:5], 0, v[134:135]
	s_add_i32 m0, s33, 0x2000
	s_nop 0
	global_load_lds_dwordx4 v[220:221], off
	v_lshl_add_u64 v[220:221], s[34:35], 0, v[128:129]
	s_mov_b32 m0, s27
	s_nop 0
	global_load_lds_dwordx4 v[220:221], off
	s_mov_b32 m0, s49
	s_nop 0
	global_load_lds_dwordx4 v[224:225], off
	s_cmp_eq_u32 s99, 0
	s_cbranch_scc1 .Lw10_1n
	s_waitcnt vmcnt(24)
	s_branch .Lw10_1d

.Lw10_1d:
	s_mov_b32 s99, 0
	s_waitcnt lgkmcnt(0)
	s_barrier
	s_setprio 1
	s_waitcnt lgkmcnt(0)
	v_mfma_f32_16x16x32_bf16 v[60:63], v[152:155], v[184:187], v[60:63]
	v_mfma_f32_16x16x32_bf16 v[56:59], v[160:163], v[184:187], v[56:59]
	v_mfma_f32_16x16x32_bf16 v[52:55], v[152:155], v[192:195], v[52:55]
	v_mfma_f32_16x16x32_bf16 v[44:47], v[160:163], v[192:195], v[44:47]
	v_mfma_f32_16x16x32_bf16 v[36:39], v[152:155], v[202:205], v[36:39]
	v_mfma_f32_16x16x32_bf16 v[28:31], v[160:163], v[202:205], v[28:31]
	v_mfma_f32_16x16x32_bf16 v[20:23], v[152:155], v[210:213], v[20:23]
	v_mfma_f32_16x16x32_bf16 v[12:15], v[160:163], v[210:213], v[12:15]
	v_mfma_f32_16x16x32_bf16 v[60:63], v[156:159], v[188:191], v[60:63]
	v_mfma_f32_16x16x32_bf16 v[56:59], v[164:167], v[188:191], v[56:59]
	v_mfma_f32_16x16x32_bf16 v[52:55], v[156:159], v[198:201], v[52:55]
	v_mfma_f32_16x16x32_bf16 v[44:47], v[164:167], v[198:201], v[44:47]
	v_mfma_f32_16x16x32_bf16 v[36:39], v[156:159], v[206:209], v[36:39]
	v_mfma_f32_16x16x32_bf16 v[28:31], v[164:167], v[206:209], v[28:31]
	v_mfma_f32_16x16x32_bf16 v[20:23], v[156:159], v[214:217], v[20:23]
	v_mfma_f32_16x16x32_bf16 v[12:15], v[164:167], v[214:217], v[12:15]
	s_setprio 0
	s_setprio 1
	v_mfma_f32_16x16x32_bf16 v[48:51], v[168:171], v[184:187], v[48:51]
	v_mfma_f32_16x16x32_bf16 v[40:43], v[176:179], v[184:187], v[40:43]
	v_mfma_f32_16x16x32_bf16 v[32:35], v[168:171], v[192:195], v[32:35]
	v_mfma_f32_16x16x32_bf16 v[24:27], v[176:179], v[192:195], v[24:27]
	v_mfma_f32_16x16x32_bf16 v[16:19], v[168:171], v[202:205], v[16:19]
	v_mfma_f32_16x16x32_bf16 v[8:11], v[176:179], v[202:205], v[8:11]
	v_mfma_f32_16x16x32_bf16 v[4:7], v[168:171], v[210:213], v[4:7]
	v_mfma_f32_16x16x32_bf16 v[0:3], v[176:179], v[210:213], v[0:3]
	v_mfma_f32_16x16x32_bf16 v[48:51], v[172:175], v[188:191], v[48:51]
	v_mfma_f32_16x16x32_bf16 v[40:43], v[180:183], v[188:191], v[40:43]
	v_mfma_f32_16x16x32_bf16 v[32:35], v[172:175], v[198:201], v[32:35]
	v_mfma_f32_16x16x32_bf16 v[24:27], v[180:183], v[198:201], v[24:27]
	v_mfma_f32_16x16x32_bf16 v[16:19], v[172:175], v[206:209], v[16:19]
	v_mfma_f32_16x16x32_bf16 v[8:11], v[180:183], v[206:209], v[8:11]
	v_mfma_f32_16x16x32_bf16 v[4:7], v[172:175], v[214:217], v[4:7]
	v_mfma_f32_16x16x32_bf16 v[0:3], v[180:183], v[214:217], v[0:3]
	s_setprio 0
	s_barrier
	s_add_i32 s33, 0, 0x18000
	s_add_i32 s40, 0, 0x1c000
	v_add_u32_e32 v164, s33, v148
	v_add_u32_e32 v180, s40, v148
	ds_read_b128 v[152:155], v164
	ds_read_b128 v[156:159], v164 offset:1024
	ds_read_b128 v[160:163], v164 offset:2048
	ds_read_b128 v[164:167], v164 offset:3072
	ds_read_b128 v[168:171], v180
	ds_read_b128 v[172:175], v180 offset:1024
	ds_read_b128 v[176:179], v180 offset:2048
	ds_read_b128 v[180:183], v180 offset:3072
	s_add_u32 s4, s34, 0x40000
	s_addc_u32 s5, s35, 0
	s_mov_b32 m0, s50
	v_lshl_add_u64 v[226:227], s[4:5], 0, v[128:129]
	ds_read_b128 v[184:187], v151 offset:32768
	ds_read_b128 v[188:191], v151 offset:33792
	ds_read_b128 v[192:195], v151 offset:34816
	ds_read_b128 v[198:201], v151 offset:35840
	ds_read_b128 v[202:205], v151 offset:36864
	ds_read_b128 v[206:209], v151 offset:37888
	ds_read_b128 v[210:213], v151 offset:38912
	ds_read_b128 v[214:217], v151 offset:39936
	global_load_lds_dwordx4 v[226:227], off
	v_lshl_add_u64 v[226:227], s[4:5], 0, v[132:133]
	s_mov_b32 m0, s51
	s_nop 0
	global_load_lds_dwordx4 v[226:227], off
	s_waitcnt vmcnt(8)
	s_waitcnt lgkmcnt(0)
	s_barrier
	s_setprio 1
	s_waitcnt lgkmcnt(0)
	v_mfma_f32_16x16x32_bf16 v[124:127], v[152:155], v[184:187], v[124:127]
	v_mfma_f32_16x16x32_bf16 v[120:123], v[160:163], v[184:187], v[120:123]
	v_mfma_f32_16x16x32_bf16 v[116:119], v[152:155], v[192:195], v[116:119]
	v_mfma_f32_16x16x32_bf16 v[108:111], v[160:163], v[192:195], v[108:111]
	v_mfma_f32_16x16x32_bf16 v[100:103], v[152:155], v[202:205], v[100:103]
	v_mfma_f32_16x16x32_bf16 v[92:95], v[160:163], v[202:205], v[92:95]
	v_mfma_f32_16x16x32_bf16 v[84:87], v[152:155], v[210:213], v[84:87]
	v_mfma_f32_16x16x32_bf16 v[76:79], v[160:163], v[210:213], v[76:79]
	v_mfma_f32_16x16x32_bf16 v[124:127], v[156:159], v[188:191], v[124:127]
	v_mfma_f32_16x16x32_bf16 v[120:123], v[164:167], v[188:191], v[120:123]
	v_mfma_f32_16x16x32_bf16 v[116:119], v[156:159], v[198:201], v[116:119]
	v_mfma_f32_16x16x32_bf16 v[108:111], v[164:167], v[198:201], v[108:111]
	v_mfma_f32_16x16x32_bf16 v[100:103], v[156:159], v[206:209], v[100:103]
	v_mfma_f32_16x16x32_bf16 v[92:95], v[164:167], v[206:209], v[92:95]
	v_mfma_f32_16x16x32_bf16 v[84:87], v[156:159], v[214:217], v[84:87]
	v_mfma_f32_16x16x32_bf16 v[76:79], v[164:167], v[214:217], v[76:79]
	s_setprio 0
	s_setprio 1
	v_mfma_f32_16x16x32_bf16 v[112:115], v[168:171], v[184:187], v[112:115]
	v_mfma_f32_16x16x32_bf16 v[104:107], v[176:179], v[184:187], v[104:107]
	v_mfma_f32_16x16x32_bf16 v[96:99], v[168:171], v[192:195], v[96:99]
	v_mfma_f32_16x16x32_bf16 v[88:91], v[176:179], v[192:195], v[88:91]
	v_mfma_f32_16x16x32_bf16 v[80:83], v[168:171], v[202:205], v[80:83]
	v_mfma_f32_16x16x32_bf16 v[72:75], v[176:179], v[202:205], v[72:75]
	v_mfma_f32_16x16x32_bf16 v[68:71], v[168:171], v[210:213], v[68:71]
	v_mfma_f32_16x16x32_bf16 v[64:67], v[176:179], v[210:213], v[64:67]
	v_mfma_f32_16x16x32_bf16 v[112:115], v[172:175], v[188:191], v[112:115]
	v_mfma_f32_16x16x32_bf16 v[104:107], v[180:183], v[188:191], v[104:107]
	v_mfma_f32_16x16x32_bf16 v[96:99], v[172:175], v[198:201], v[96:99]
	v_mfma_f32_16x16x32_bf16 v[88:91], v[180:183], v[198:201], v[88:91]
	v_mfma_f32_16x16x32_bf16 v[80:83], v[172:175], v[206:209], v[80:83]
	v_mfma_f32_16x16x32_bf16 v[72:75], v[180:183], v[206:209], v[72:75]
	v_mfma_f32_16x16x32_bf16 v[68:71], v[172:175], v[214:217], v[68:71]
	v_mfma_f32_16x16x32_bf16 v[64:67], v[180:183], v[214:217], v[64:67]
	s_setprio 0
	s_barrier
	s_add_i32 s4, s33, s46
	v_lshl_add_u64 v[144:145], v[144:145], 0, s[14:15]
	s_mov_b32 m0, s4
	ds_read_b128 v[184:187], v151 offset:49152
	ds_read_b128 v[188:191], v151 offset:50176
	ds_read_b128 v[192:195], v151 offset:51200
	ds_read_b128 v[198:201], v151 offset:52224
	ds_read_b128 v[202:205], v151 offset:53248
	ds_read_b128 v[206:209], v151 offset:54272
	ds_read_b128 v[210:213], v151 offset:55296
	ds_read_b128 v[214:217], v151 offset:56320
	global_load_lds_dwordx4 v[144:145], off
	s_add_i32 m0, s4, 0x2000
	s_add_u32 s4, s30, 0x40080
	v_lshl_add_u64 v[144:145], v[218:219], 0, s[14:15]
	s_addc_u32 s5, s31, 0
	s_add_i32 s30, s40, s46
	global_load_lds_dwordx4 v[144:145], off
	v_lshl_add_u64 v[144:145], s[4:5], 0, v[130:131]
	s_mov_b32 m0, s30
	s_nop 0
	global_load_lds_dwordx4 v[144:145], off
	v_lshl_add_u64 v[144:145], s[4:5], 0, v[134:135]
	s_add_i32 m0, s30, 0x2000
	s_nop 0
	global_load_lds_dwordx4 v[144:145], off
	v_lshl_add_u64 v[144:145], v[220:221], 0, s[14:15]
	s_mov_b32 m0, s56
	s_nop 0
	global_load_lds_dwordx4 v[144:145], off
	v_lshl_add_u64 v[144:145], v[224:225], 0, s[14:15]
	s_mov_b32 m0, s57
	s_nop 0
	global_load_lds_dwordx4 v[144:145], off
	s_waitcnt vmcnt(8)
	s_waitcnt lgkmcnt(0)
	s_barrier
	s_setprio 1
	s_waitcnt lgkmcnt(0)
	v_mfma_f32_16x16x32_bf16 v[60:63], v[152:155], v[184:187], v[60:63]
	v_mfma_f32_16x16x32_bf16 v[56:59], v[160:163], v[184:187], v[56:59]
	v_mfma_f32_16x16x32_bf16 v[52:55], v[152:155], v[192:195], v[52:55]
	v_mfma_f32_16x16x32_bf16 v[44:47], v[160:163], v[192:195], v[44:47]
	v_mfma_f32_16x16x32_bf16 v[36:39], v[152:155], v[202:205], v[36:39]
	v_mfma_f32_16x16x32_bf16 v[28:31], v[160:163], v[202:205], v[28:31]
	v_mfma_f32_16x16x32_bf16 v[20:23], v[152:155], v[210:213], v[20:23]
	v_mfma_f32_16x16x32_bf16 v[12:15], v[160:163], v[210:213], v[12:15]
	v_mfma_f32_16x16x32_bf16 v[60:63], v[156:159], v[188:191], v[60:63]
	v_mfma_f32_16x16x32_bf16 v[56:59], v[164:167], v[188:191], v[56:59]
	v_mfma_f32_16x16x32_bf16 v[52:55], v[156:159], v[198:201], v[52:55]
	v_mfma_f32_16x16x32_bf16 v[44:47], v[164:167], v[198:201], v[44:47]
	v_mfma_f32_16x16x32_bf16 v[36:39], v[156:159], v[206:209], v[36:39]
	v_mfma_f32_16x16x32_bf16 v[28:31], v[164:167], v[206:209], v[28:31]
	v_mfma_f32_16x16x32_bf16 v[20:23], v[156:159], v[214:217], v[20:23]
	v_mfma_f32_16x16x32_bf16 v[12:15], v[164:167], v[214:217], v[12:15]
	s_setprio 0
	s_setprio 1
	v_mfma_f32_16x16x32_bf16 v[48:51], v[168:171], v[184:187], v[48:51]
	v_mfma_f32_16x16x32_bf16 v[40:43], v[176:179], v[184:187], v[40:43]
	v_mfma_f32_16x16x32_bf16 v[32:35], v[168:171], v[192:195], v[32:35]
	v_mfma_f32_16x16x32_bf16 v[24:27], v[176:179], v[192:195], v[24:27]
	v_mfma_f32_16x16x32_bf16 v[16:19], v[168:171], v[202:205], v[16:19]
	v_mfma_f32_16x16x32_bf16 v[8:11], v[176:179], v[202:205], v[8:11]
	v_mfma_f32_16x16x32_bf16 v[4:7], v[168:171], v[210:213], v[4:7]
	v_mfma_f32_16x16x32_bf16 v[0:3], v[176:179], v[210:213], v[0:3]
	v_mfma_f32_16x16x32_bf16 v[48:51], v[172:175], v[188:191], v[48:51]
	v_mfma_f32_16x16x32_bf16 v[40:43], v[180:183], v[188:191], v[40:43]
	v_mfma_f32_16x16x32_bf16 v[32:35], v[172:175], v[198:201], v[32:35]
	v_mfma_f32_16x16x32_bf16 v[24:27], v[180:183], v[198:201], v[24:27]
	v_mfma_f32_16x16x32_bf16 v[16:19], v[172:175], v[206:209], v[16:19]
	v_mfma_f32_16x16x32_bf16 v[8:11], v[180:183], v[206:209], v[8:11]
	v_mfma_f32_16x16x32_bf16 v[4:7], v[172:175], v[214:217], v[4:7]
	v_mfma_f32_16x16x32_bf16 v[0:3], v[180:183], v[214:217], v[0:3]
	s_setprio 0
	s_barrier
	s_add_i32 s67, s67, 2
	s_add_u32 s65, s65, 0x100
	s_addc_u32 s66, s66, 0
	s_add_u32 s28, s28, 0x100
	s_addc_u32 s29, s29, 0
	s_cmp_gt_u32 s67, 13
	s_cbranch_scc0 .LBB0_875
	s_and_b64 vcc, exec, s[16:17]
	s_cbranch_vccz .LBB0_878
	s_barrier
.LBB0_878:
	s_mov_b32 s99, 1
	s_lshl_b32 s4, s62, 8
	s_add_i32 s5, s4, 0xfffff500
	s_cmp_lt_i32 s62, 11
	s_cselect_b32 s19, s60, 0x23200e00
	s_cselect_b32 s21, s4, s5
	s_add_u32 s4, s10, s19
	s_addc_u32 s5, s11, 0
	s_lshl_b32 s19, s26, 8
	v_mov_b32_e32 v144, v146
	v_mov_b32_e32 v145, v147
	s_add_i32 s19, s19, s54
	v_cvt_pk_bf16_f32 v68, v68, v69
	v_cvt_pk_bf16_f32 v69, v70, v71
	v_cvt_pk_bf16_f32 v70, v64, v65
	v_cvt_pk_bf16_f32 v124, v124, v125
	v_cvt_pk_bf16_f32 v125, v126, v127
	s_nop 0
	v_add_u32_e32 v156, s19, v144
	s_or_b32 s19, s21, s55
	v_lshl_add_u32 v152, v145, 3, s19
	v_mov_b64_e32 v[144:145], s[4:5]
	v_ashrrev_i32_e32 v153, 31, v152
	v_add_u32_e32 v64, 0x80, v156
	v_mad_i64_i32 v[154:155], s[4:5], v156, s61, v[144:145]
	v_cvt_pk_bf16_f32 v126, v120, v121
	v_lshlrev_b64 v[120:121], 1, v[152:153]
	v_mad_i64_i32 v[64:65], s[4:5], v64, s61, v[144:145]
	v_cvt_pk_bf16_f32 v127, v122, v123
	v_lshl_add_u64 v[122:123], v[154:155], 0, v[120:121]
	v_cvt_pk_bf16_f32 v112, v112, v113
	v_cvt_pk_bf16_f32 v113, v114, v115
	v_cvt_pk_bf16_f32 v114, v104, v105
	v_add_u32_e32 v104, 16, v156
	v_cvt_pk_bf16_f32 v60, v60, v61
	v_cvt_pk_bf16_f32 v61, v62, v63
	v_cvt_pk_bf16_f32 v62, v56, v57
	v_lshl_add_u64 v[56:57], v[64:65], 0, v[120:121]
	v_cvt_pk_bf16_f32 v48, v48, v49
	v_cvt_pk_bf16_f32 v49, v50, v51
	v_cvt_pk_bf16_f32 v50, v40, v41
	v_add_u32_e32 v40, 0x90, v156
	v_cvt_pk_bf16_f32 v115, v106, v107
	flat_store_dwordx4 v[122:123], v[112:115] offset:256
	v_cvt_pk_bf16_f32 v51, v42, v43
	flat_store_dwordx4 v[56:57], v[48:51] offset:256
	v_cvt_pk_bf16_f32 v106, v108, v109
	v_cvt_pk_bf16_f32 v96, v96, v97
	v_cvt_pk_bf16_f32 v97, v98, v99
	s_nop 0
	v_mad_i64_i32 v[112:113], s[4:5], v104, s61, v[144:145]
	v_mad_i64_i32 v[48:49], s[4:5], v40, s61, v[144:145]
	v_lshl_add_u64 v[108:109], v[112:113], 0, v[120:121]
	v_cvt_pk_bf16_f32 v98, v88, v89
	v_add_u32_e32 v88, 32, v156
	v_cvt_pk_bf16_f32 v42, v44, v45
	v_lshl_add_u64 v[44:45], v[48:49], 0, v[120:121]
	v_cvt_pk_bf16_f32 v32, v32, v33
	v_cvt_pk_bf16_f32 v33, v34, v35
	v_cvt_pk_bf16_f32 v34, v24, v25
	v_add_u32_e32 v24, 0xa0, v156
	v_cvt_pk_bf16_f32 v99, v90, v91
	flat_store_dwordx4 v[108:109], v[96:99] offset:256
	v_cvt_pk_bf16_f32 v35, v26, v27
	flat_store_dwordx4 v[44:45], v[32:35] offset:256
	v_cvt_pk_bf16_f32 v90, v92, v93
	v_cvt_pk_bf16_f32 v80, v80, v81
	v_cvt_pk_bf16_f32 v81, v82, v83
	s_nop 0
	v_mad_i64_i32 v[96:97], s[4:5], v88, s61, v[144:145]
	v_mad_i64_i32 v[32:33], s[4:5], v24, s61, v[144:145]
	v_lshl_add_u64 v[92:93], v[96:97], 0, v[120:121]
	v_cvt_pk_bf16_f32 v82, v72, v73
	v_add_u32_e32 v72, 48, v156
	v_cvt_pk_bf16_f32 v26, v28, v29
	v_lshl_add_u64 v[28:29], v[32:33], 0, v[120:121]
	v_cvt_pk_bf16_f32 v16, v16, v17
	v_cvt_pk_bf16_f32 v17, v18, v19
	v_cvt_pk_bf16_f32 v18, v8, v9
	v_add_u32_e32 v8, 0xb0, v156
	v_cvt_pk_bf16_f32 v83, v74, v75
	flat_store_dwordx4 v[92:93], v[80:83] offset:256
	v_cvt_pk_bf16_f32 v19, v10, v11
	flat_store_dwordx4 v[28:29], v[16:19] offset:256
	v_cvt_pk_bf16_f32 v74, v76, v77
	v_cvt_pk_bf16_f32 v10, v12, v13
	s_andn2_b64 vcc, exec, s[6:7]
	v_mad_i64_i32 v[80:81], s[4:5], v72, s61, v[144:145]
	v_mad_i64_i32 v[16:17], s[4:5], v8, s61, v[144:145]
	v_lshl_add_u64 v[76:77], v[80:81], 0, v[120:121]
	v_lshl_add_u64 v[12:13], v[16:17], 0, v[120:121]
	s_mov_b64 s[6:7], -1
	flat_store_dwordx4 v[122:123], v[124:127]
	v_cvt_pk_bf16_f32 v104, v116, v117
	v_cvt_pk_bf16_f32 v105, v118, v119
	v_cvt_pk_bf16_f32 v107, v110, v111
	flat_store_dwordx4 v[108:109], v[104:107]
	v_cvt_pk_bf16_f32 v88, v100, v101
	v_cvt_pk_bf16_f32 v89, v102, v103
	v_cvt_pk_bf16_f32 v91, v94, v95
	flat_store_dwordx4 v[92:93], v[88:91]
	v_cvt_pk_bf16_f32 v72, v84, v85
	v_cvt_pk_bf16_f32 v73, v86, v87
	v_cvt_pk_bf16_f32 v75, v78, v79
	flat_store_dwordx4 v[76:77], v[72:75]
	v_cvt_pk_bf16_f32 v71, v66, v67
	flat_store_dwordx4 v[76:77], v[68:71] offset:256
	v_cvt_pk_bf16_f32 v63, v58, v59
	flat_store_dwordx4 v[56:57], v[60:63]
	v_cvt_pk_bf16_f32 v40, v52, v53
	v_cvt_pk_bf16_f32 v41, v54, v55
	v_cvt_pk_bf16_f32 v43, v46, v47
	flat_store_dwordx4 v[44:45], v[40:43]
	v_cvt_pk_bf16_f32 v24, v36, v37
	v_cvt_pk_bf16_f32 v25, v38, v39
	v_cvt_pk_bf16_f32 v27, v30, v31
	flat_store_dwordx4 v[28:29], v[24:27]
	v_cvt_pk_bf16_f32 v8, v20, v21
	v_cvt_pk_bf16_f32 v9, v22, v23
	v_cvt_pk_bf16_f32 v11, v14, v15
	flat_store_dwordx4 v[12:13], v[8:11]
	v_cvt_pk_bf16_f32 v4, v4, v5
	v_cvt_pk_bf16_f32 v5, v6, v7
	v_cvt_pk_bf16_f32 v6, v0, v1
	v_cvt_pk_bf16_f32 v7, v2, v3
	flat_store_dwordx4 v[12:13], v[4:7] offset:256
	s_cbranch_vccnz .LBB0_871
	s_andn2_b64 vcc, exec, s[12:13]
	s_cbranch_vccnz .LBB0_870
	s_barrier
	s_branch .LBB0_870
